# P12 sample down GEMM split in K over 32 workgroups (2 per tile, f32 partial hand-off through ws, per-wave flag)
# speedup vs baseline: 1.0193x; 1.0193x over previous
; #define PH(k) if (a.ph_lo <= (k) && (k) < a.ph_hi) { if ((k) > a.ph_lo && (k) != 6) SEAM(k);
; #define GEMM_N1024(EPI, Aoff, Woff, Mrows, Kdim, rowbase, Gn, cid, ...) do { pg8::Gemm g{(const bf16_t*)(a.ws + (Aoff)) + (size_t)(rowbase) * (Kdim), (const bf16_t*)(a.ws + (Woff)), (Mrows), 1024, (Kdim)}; \
;         pg8::StaticOrder S; S.init((Mrows), 1024, (Gn), (cid)); EPI E{__VA_ARGS__, (rowbase)}; pg8::gemm_phase<EPI, pg8::StaticOrder, false, true>(lds, g, S, E); } while (0)
; template <bool DRYR = false>
; __device__ __forceinline__ void row_pass2(const Args& a, int row_lo, int row_hi, int gw, int NGW, int lane) {
;     ...
;     f32x4 gp[4];
; #pragma unroll
;     for (int j = 0; j < 4; ++j) gp[j] = ((const f32x4*)a.in[I_NFPOST])[lane + 64 * j];
;     for (int r0 = row_lo + 2 * gw; r0 < row_hi; r0 += 2 * NGW) {
; __global__ void __launch_bounds__(512) fwd_kernel(Args a) {
;     ...
;     PH(12) {
;         if (G >= 32 && bx < 16) GEMM_N1024(EpiN1024<2>, A_HID, WS_WDN, MS, DFF, MP, 16, bx, (bf16_t*)(a.ws + A_GA), nullptr, (float*)(a.ws + WS_RSS2));
;         else if (G >= 32) row_pass2(a, 0, MP, gw - 128, NGW - 128, lane);
;         else { row_pass2(a, 0, MP, gw, NGW, lane); GEMM_N1024(EpiN1024<2>, A_HID, WS_WDN, MS, DFF, MP, G, bx, (bf16_t*)(a.ws + A_GA), nullptr, (float*)(a.ws + WS_RSS2)); }
.LBB0_1362:
	s_cmp_lt_i32 s58, 32
	s_cselect_b64 s[0:1], -1, 0
	s_cmp_gt_i32 s58, 31
	s_cselect_b64 s[8:9], -1, 0
	s_cmp_lt_i32 s2, 32
	s_cselect_b64 s[4:5], -1, 0
	s_and_b64 s[8:9], s[4:5], s[8:9]
	s_andn2_b64 vcc, exec, s[8:9]
	s_mov_b64 s[8:9], -1
	s_cbranch_vccz .LBB0_1420
	v_lshlrev_b32_e32 v144, 4, v176
	global_load_dwordx4 v[0:3], v144, s[12:13]
	s_waitcnt lgkmcnt(0)
	global_load_dwordx4 v[4:7], v144, s[12:13] offset:1024
	global_load_dwordx4 v[8:11], v144, s[12:13] offset:2048
	global_load_dwordx4 v[12:15], v144, s[12:13] offset:3072
	s_add_u32 s8, s54, 0x2291000
	s_addc_u32 s9, s55, 0
	s_mov_b64 s[10:11], -1
	s_and_b64 vcc, exec, s[0:1]
	s_cbranch_vccz .LBB0_1413
	s_cmpk_gt_i32 s81, 0x1fff
	s_cbranch_scc1 .LBB0_1369
	v_mov_b32_e32 v145, 0
	s_lshl_b32 s0, s81, 1
	s_waitcnt vmcnt(0)
	v_lshlrev_b32_e32 v16, 3, v176
	v_mov_b32_e32 v17, v145
	v_lshl_add_u64 v[18:19], s[54:55], 0, v[16:17]
	s_mov_b64 s[10:11], 0xbc00000
	s_ashr_i32 s1, s0, 31
	v_lshl_add_u64 v[34:35], v[18:19], 0, s[10:11]
	s_lshl_b32 s10, s58, 4
	s_lshl_b64 s[14:15], s[0:1], 12
	s_add_u32 s14, s52, s14
	s_addc_u32 s15, s53, s15
	v_lshl_add_u64 v[18:19], s[14:15], 0, v[144:145]
	s_mov_b64 s[14:15], 0x1000
	s_ashr_i32 s11, s10, 31
	v_lshl_add_u64 v[36:37], v[18:19], 0, s[14:15]
	s_lshl_b64 s[14:15], s[10:11], 12
	s_lshl_b64 s[16:17], s[0:1], 2
	s_add_u32 s20, s16, 0x2291000
	s_addc_u32 s21, s17, 0
	s_lshl_b64 s[18:19], s[0:1], 11
	v_lshl_add_u64 v[32:33], s[52:53], 0, v[144:145]
	s_lshl_b64 s[16:17], s[10:11], 2
	v_or_b32_e32 v38, s18, v16
	v_mov_b32_e32 v39, s19
	s_lshl_b64 s[18:19], s[10:11], 11
	s_mov_b32 s1, 0xbc00000
	v_mov_b32_e32 v48, 0x358637bd
	s_mov_b32 s3, 0x800000
	s_branch .LBB0_1367

; template <bool DRYR = false>
; __device__ __forceinline__ void row_pass2(const Args& a, int row_lo, int row_hi, int gw, int NGW, int lane) {
;     const bf16_t* F = (const bf16_t*)(a.ws + A_GA); const float* rss = (const float*)(a.ws + WS_RSS2); float* XO = a.out + O_Y;
;     f32x4 gp[4];
; #pragma unroll
;     for (int j = 0; j < 4; ++j) gp[j] = ((const f32x4*)a.in[I_NFPOST])[lane + 64 * j];
;     for (int r0 = row_lo + 2 * gw; r0 < row_hi; r0 += 2 * NGW) {
;         f32x4 xv[2][4]; u32x2 fv[2][4]; float rs[2];
; #pragma unroll
;         for (int r = 0; r < 2; ++r) { const int row = (r0 + r < row_hi) ? r0 + r : r0; rs[r] = rss[row];
;             const f32x4* xo = (const f32x4*)(XO + (size_t)row * DM) + lane; const u32x2* fr = (const u32x2*)(F + (size_t)row * DM) + lane;
.LBB0_1413:
	s_and_b64 vcc, exec, s[10:11]
	s_cbranch_vccz .LBB0_1419
	s_lshl_b32 s0, s81, 1
	s_addk_i32 s0, 0xfe00
	s_cmpk_gt_i32 s0, 0x3fff
	s_cbranch_scc1 .LBB0_1419
	v_mov_b32_e32 v145, 0
	s_waitcnt vmcnt(0)
	v_lshlrev_b32_e32 v16, 3, v176
	v_mov_b32_e32 v17, v145
	v_lshl_add_u64 v[18:19], s[54:55], 0, v[16:17]
	s_mov_b64 s[4:5], 0xbc00000
	s_lshl_b32 s1, s58, 4
	v_lshl_add_u64 v[34:35], v[18:19], 0, s[4:5]
	s_add_i32 s4, s1, 0xfffffe00
	s_ashr_i32 s1, s0, 31
	s_lshl_b64 s[10:11], s[0:1], 12
	s_add_u32 s10, s52, s10
	s_addc_u32 s11, s53, s11
	v_lshl_add_u64 v[18:19], s[10:11], 0, v[144:145]
	s_mov_b64 s[10:11], 0x1000
	s_ashr_i32 s5, s4, 31
	v_lshl_add_u64 v[36:37], v[18:19], 0, s[10:11]
	s_lshl_b64 s[10:11], s[4:5], 12
	s_lshl_b64 s[14:15], s[0:1], 2
	s_add_u32 s18, s14, 0x2291000
	s_addc_u32 s19, s15, 0
	s_lshl_b64 s[16:17], s[0:1], 11
	v_lshl_add_u64 v[32:33], s[52:53], 0, v[144:145]
	s_lshl_b64 s[14:15], s[4:5], 2
	v_or_b32_e32 v38, s16, v16
	v_mov_b32_e32 v39, s17
	s_lshl_b64 s[16:17], s[4:5], 11
	s_mov_b32 s1, 0xbc00000
	v_mov_b32_e32 v48, 0x358637bd
	s_mov_b32 s3, 0x800000
	s_branch .LBB0_1417

;     __host__ __device__ bool next(int i, Unit& u) const {
;         const long L = (long)i * G + c; if (L >= nwg) return false;
;         int wgid = (int)L; { const int q = nwg / NXCD, r = nwg % NXCD, xcd = wgid % NXCD, off = wgid / NXCD; wgid = (xcd < r ? xcd * (q + 1) : r * (q + 1) + (xcd - r) * q) + off; }
;         const int nig = WGM * nN, gid = wgid / nig, fm = gid * WGM, gsz = (nM - fm) < WGM ? (nM - fm) : WGM;
;         u.pm = fm + ((wgid % nig) % gsz); u.pn = (wgid % nig) / gsz; return true;
.LBB0_1420:
	s_andn2_b64 vcc, exec, s[8:9]
	s_cbranch_vccnz .LBB0_1460
	s_and_b32 s98, s2, 15
	s_ashr_i32 s28, s2, 31
	s_lshr_b32 s0, s28, 29
	s_add_i32 s4, s98, s0
	s_and_b32 s0, s4, -8
	s_sub_i32 s3, s98, s0
	s_cmp_gt_i32 s3, -1
	v_readfirstlane_b32 s29, v178
	s_cbranch_scc0 .LBB0_1423
	s_lshl_b32 s5, s3, 1
	s_cbranch_execz .LBB0_1424
	s_branch .LBB0_1425

; #define PG8_STAGE(bufoff, gbase, voff) do { _Pragma("unroll") for (int _i = 0; _i < 2; ++_i) \
;         __builtin_amdgcn_global_load_lds((const unsigned*)((const char*)(gbase) + (voff)[_i]), (PG8_LAS unsigned*)(lds + (bufoff) + ldsw + _i * 8192), 16, 0, 0); } while (0)
; #define PG8_WAIT_V(n) asm volatile("s_waitcnt vmcnt(" #n ")" ::: "memory")
; #define PG8_BAR __builtin_amdgcn_s_barrier()
; template <class Epi, class Sched, bool ALIGN_EPI = false, bool SP2 = false>
; __device__ __forceinline__ void gemm_phase(PG8_LAS unsigned char* lds, const Gemm g, const Sched& S, const Epi& E) {
;     ...
;     for (int i = 0; i < 2; ++i) { int R, C; stage_rc(tid * 16 + i * 8192, R, C); const int Rb = Epi::PERM ? ((R & ~31) + perm32(R & 31)) : R;
;         voffA[i] = (unsigned)(R * K + C) * 2u; voffB[i] = (unsigned)(Rb * K + C) * 2u; }
;     ...
;     const char* cA = (const char*)g.A + (size_t)cur.pm * tstep; const char* cB = (const char*)g.Bt + (size_t)cur.pn * tstep;
;     S.a_ready(cur);
;     if constexpr (SP2) {
;         PG8_STAGE(PG8_SB(0, 0), cB, voffB); PG8_STAGE(PG8_SB(0, 1), cB + hstep, voffB); PG8_STAGE(PG8_SA(0, 0), cA, voffA); PG8_STAGE(PG8_SA(0, 1), cA + hstep, voffA);
;         if (wr == 1) PG8_BAR;
;         PG8_WAIT_V(2); PG8_BAR;
;         PG8_STAGE(PG8_SB(1, 0), cB + kstep, voffB); PG8_STAGE(PG8_SA(1, 0), cA + kstep, voffA); PG8_STAGE(PG8_SB(1, 1), cB + hstep + kstep, voffB);
;         PG8_WAIT_V(6); PG8_BAR;
.LBB0_1425:
	s_add_u32 s30, s54, 0x7b00000
	s_waitcnt vmcnt(0)
	v_lshlrev_b32_e32 v0, 4, v178
	v_and_b32_e32 v1, 32, v178
	s_addc_u32 s31, s55, 0
	v_bfe_u32 v2, v178, 2, 4
	v_bitop3_b32 v8, v0, v1, 48 bitop3:0x6c
	v_lshrrev_b32_e32 v3, 3, v178
	s_movk_i32 s0, 0x70
	v_add_u32_e32 v0, 0x2000, v0
	s_add_u32 s34, s54, 0x1d00000
	v_and_or_b32 v3, v3, s0, v2
	v_lshrrev_b32_e32 v0, 7, v0
	s_movk_i32 s0, 0xf0
	s_addc_u32 s35, s55, 0
	s_lshr_b32 s99, s2, 4
	s_mul_i32 s99, s99, 0xb00
	s_add_u32 s30, s30, s99
	s_addc_u32 s31, s31, 0
	s_add_u32 s34, s34, s99
	s_addc_u32 s35, s35, 0
	v_and_or_b32 v0, v0, s0, v2
	s_ashr_i32 s0, s4, 3
	s_add_i32 s0, s5, s0
	s_ashr_i32 s4, s0, 31
	s_lshr_b32 s4, s4, 27
	s_add_i32 s4, s0, s4
	s_ashr_i32 s4, s4, 5
	s_lshl_b32 s8, s4, 3
	v_and_b32_e32 v9, 64, v178
	s_sub_i32 s5, 4, s8
	s_lshl_b32 s4, s4, 5
	v_or_b32_e32 v1, v8, v9
	v_mul_u32_u24_e32 v10, 0x1600, v3
	v_mul_u32_u24_e32 v11, 0x1600, v0
	s_min_u32 s9, s5, 8
	s_sub_i32 s10, s0, s4
	v_or_b32_e32 v128, v10, v1
	v_or_b32_e32 v130, v11, v1
	s_sext_i32_i8 s0, s10
	v_cvt_f32_ubyte0_e32 v1, s9
	v_cvt_f32_i32_e32 v0, s0
	v_rcp_iflag_f32_e32 v2, v1
	s_lshr_b32 s3, s29, 6
	s_ashr_i32 s0, s0, 30
	s_lshr_b32 s1, s29, 8
	v_mul_f32_e32 v2, v0, v2
	v_trunc_f32_e32 v2, v2
	v_fma_f32 v0, -v2, v1, v0
	v_cvt_i32_f32_e32 v2, v2
	s_lshl_b32 s36, s3, 10
	s_or_b32 s0, s0, 1
	v_cmp_ge_f32_e64 s[4:5], |v0|, v1
	s_and_b64 s[4:5], s[4:5], exec
	s_cselect_b32 s0, s0, 0
	v_readfirstlane_b32 s4, v2
	s_add_i32 s0, s4, s0
	s_mul_i32 s4, s0, s9
	s_sub_i32 s4, s10, s4
	s_sext_i32_i8 s4, s4
	s_add_i32 s47, s8, s4
	s_bfe_i64 s[4:5], s[0:1], 0x80000
	s_mul_hi_i32 s5, s4, 0x160000
	s_mul_i32 s4, s4, 0x160000
	s_add_u32 s24, s34, s4
	s_addc_u32 s25, s35, s5
	s_add_i32 s37, s36, 0
	s_add_i32 m0, s37, 0x10000
	s_mul_i32 s9, s47, 0x160000
	global_load_lds_dwordx4 v128, s[24:25]
	s_add_i32 m0, s37, 0x12000
	s_add_u32 s4, s24, 0xb0000
	global_load_lds_dwordx4 v130, s[24:25]
	s_addc_u32 s5, s25, 0
	s_add_i32 m0, s37, 0x14000
	s_mul_hi_i32 s8, s47, 0x160000
	global_load_lds_dwordx4 v128, s[4:5]
	s_add_i32 m0, s37, 0x16000
	s_add_u32 s22, s30, s9
	s_addc_u32 s23, s31, s8
	s_add_i32 s38, s37, 0x2000
	global_load_lds_dwordx4 v130, s[4:5]
	s_mov_b32 m0, s37
	s_add_u32 s4, s22, 0xb0000
	global_load_lds_dwordx4 v128, s[22:23]
	s_mov_b32 m0, s38
	s_addc_u32 s5, s23, 0
	s_add_i32 s39, s37, 0x4000
	global_load_lds_dwordx4 v130, s[22:23]
	s_mov_b32 m0, s39
	s_add_i32 s40, s37, 0x6000
	global_load_lds_dwordx4 v128, s[4:5]
	s_mov_b32 m0, s40
	v_mov_b32_e32 v129, 0
	global_load_lds_dwordx4 v130, s[4:5]
	v_mov_b32_e32 v131, v129
	s_mov_b32 s9, 0
	v_lshl_add_u64 v[6:7], s[24:25], 0, v[128:129]
	s_waitcnt lgkmcnt(0)
	v_lshl_add_u64 v[4:5], s[24:25], 0, v[130:131]
	v_lshl_add_u64 v[2:3], s[22:23], 0, v[128:129]
	s_cmp_lg_u32 s1, 1
	v_lshl_add_u64 v[0:1], s[22:23], 0, v[130:131]
	s_cbranch_scc1 .LBB0_1427
	s_barrier

; #define PG8_STAGE(bufoff, gbase, voff) do { _Pragma("unroll") for (int _i = 0; _i < 2; ++_i) \
;         __builtin_amdgcn_global_load_lds((const unsigned*)((const char*)(gbase) + (voff)[_i]), (PG8_LAS unsigned*)(lds + (bufoff) + ldsw + _i * 8192), 16, 0, 0); } while (0)
; #define PG8_LDA(dst, b, h) do { _Pragma("unroll") for (int m = 0; m < 4; ++m) _Pragma("unroll") for (int k = 0; k < 2; ++k) dst[m][k] = *(const PG8_LAS bf16x8*)(lds + PG8_SA(b, h) + aoff + m * 2048 + k * 1024); } while (0)
; #define PG8_LDB(dst, b, h) do { _Pragma("unroll") for (int n = 0; n < 2; ++n) _Pragma("unroll") for (int k = 0; k < 2; ++k) dst[n][k] = *(const PG8_LAS bf16x8*)(lds + PG8_SB(b, h) + boff + n * 2048 + k * 1024); } while (0)
; #define PG8_MMA(ai, bj, At, Bt) do { __builtin_amdgcn_s_setprio(1); _Pragma("unroll") for (int m = 0; m < 4; ++m) _Pragma("unroll") for (int n = 0; n < 2; ++n) _Pragma("unroll") for (int k = 0; k < 2; ++k) \
;         acc[ai][bj][m][n] = __builtin_amdgcn_mfma_f32_16x16x32_bf16(Bt[n][k], At[m][k], acc[ai][bj][m][n], 0, 0, 0); __builtin_amdgcn_s_setprio(0); } while (0)
; #define PG8_WAIT_V(n) asm volatile("s_waitcnt vmcnt(" #n ")" ::: "memory")
; #define PG8_BAR __builtin_amdgcn_s_barrier()
; template <class Epi, class Sched, bool ALIGN_EPI = false, bool SP2 = false>
; __device__ __forceinline__ void gemm_phase(PG8_LAS unsigned char* lds, const Gemm g, const Sched& S, const Epi& E) {
;     ...
;         for (int t = 0; t < nt; t += 2) {
;             const bool last = (t == nt - 2);
;             const char* a1 = cA + (size_t)(t + 1) * kstep;
;             const char* a2 = last ? nA : cA + (size_t)(t + 2) * kstep; const char* b2 = last ? nB : cB + (size_t)(t + 2) * kstep;
;             const char* a3 = a2 + kstep; const char* b3 = b2 + kstep;
;             if (last && has_next) S.a_ready(nxt);
;             if constexpr (SP2) {
;             PG8_LDB(B0, 0, 0); PG8_LDB(B1, 0, 1); PG8_SCHED; PG8_LDA(At, 0, 0); PG8_STAGE(PG8_SA(1, 1), a1 + hstep, voffA);
;             PG8_WAIT_V(8); PG8_WAIT_L(0); PG8_BAR; PG8_MMA(0, 0, At, B0); PG8_MMA(0, 1, At, B1); PG8_BAR; PG8_SCHED;
;             PG8_LDA(At, 0, 1); PG8_STAGE(PG8_SB(0, 0), b2, voffB); PG8_STAGE(PG8_SB(0, 1), b2 + hstep, voffB); PG8_STAGE(PG8_SA(0, 0), a2, voffA);
;             PG8_WAIT_V(8); PG8_WAIT_L(0); PG8_BAR; PG8_MMA(1, 0, At, B0); PG8_MMA(1, 1, At, B1); PG8_BAR; PG8_SCHED;
.LBB0_1440:
	ds_read_b128 v[136:139], v143
	ds_read_b128 v[148:151], v143 offset:1024
	ds_read_b128 v[152:155], v143 offset:2048
	ds_read_b128 v[156:159], v143 offset:3072
	ds_read_b128 v[160:163], v144
	ds_read_b128 v[164:167], v144 offset:1024
	ds_read_b128 v[168:171], v144 offset:2048
	ds_read_b128 v[172:175], v144 offset:3072
	s_add_u32 s3, s22, 0xfff50080
	s_addc_u32 s24, s23, -1
	s_cmp_eq_u32 s51, 18
	s_cselect_b32 s27, s21, s24
	s_cselect_b32 s26, s20, s3
	s_cselect_b32 s25, s5, s50
	s_cselect_b32 s24, s4, s49
	v_lshl_add_u64 v[212:213], s[22:23], 0, v[132:133]
	s_add_i32 m0, s37, 0xc000
	ds_read_b128 v[180:183], v145
	ds_read_b128 v[184:187], v145 offset:1024
	ds_read_b128 v[188:191], v145 offset:2048
	ds_read_b128 v[192:195], v145 offset:3072
	ds_read_b128 v[196:199], v145 offset:4096
	ds_read_b128 v[200:203], v145 offset:5120
	ds_read_b128 v[204:207], v145 offset:6144
	ds_read_b128 v[208:211], v145 offset:7168
	global_load_lds_dwordx4 v[212:213], off
	v_lshl_add_u64 v[212:213], s[22:23], 0, v[134:135]
	s_add_i32 m0, s37, 0xe000
	s_nop 0
	global_load_lds_dwordx4 v[212:213], off
	s_waitcnt vmcnt(8)
	s_waitcnt lgkmcnt(0)
	s_barrier
	s_setprio 1
	s_waitcnt lgkmcnt(0)
	v_mfma_f32_16x16x32_bf16 v[124:127], v[136:139], v[180:183], v[124:127]
	v_mfma_f32_16x16x32_bf16 v[120:123], v[152:155], v[180:183], v[120:123]
	v_mfma_f32_16x16x32_bf16 v[112:115], v[136:139], v[188:191], v[112:115]
	v_mfma_f32_16x16x32_bf16 v[104:107], v[152:155], v[188:191], v[104:107]
	v_mfma_f32_16x16x32_bf16 v[96:99], v[136:139], v[196:199], v[96:99]
	v_mfma_f32_16x16x32_bf16 v[88:91], v[152:155], v[196:199], v[88:91]
	v_mfma_f32_16x16x32_bf16 v[80:83], v[136:139], v[204:207], v[80:83]
	v_mfma_f32_16x16x32_bf16 v[72:75], v[152:155], v[204:207], v[72:75]
	v_mfma_f32_16x16x32_bf16 v[124:127], v[148:151], v[184:187], v[124:127]
	v_mfma_f32_16x16x32_bf16 v[120:123], v[156:159], v[184:187], v[120:123]
	v_mfma_f32_16x16x32_bf16 v[112:115], v[148:151], v[192:195], v[112:115]
	v_mfma_f32_16x16x32_bf16 v[104:107], v[156:159], v[192:195], v[104:107]
	v_mfma_f32_16x16x32_bf16 v[96:99], v[148:151], v[200:203], v[96:99]
	v_mfma_f32_16x16x32_bf16 v[88:91], v[156:159], v[200:203], v[88:91]
	v_mfma_f32_16x16x32_bf16 v[80:83], v[148:151], v[208:211], v[80:83]
	v_mfma_f32_16x16x32_bf16 v[72:75], v[156:159], v[208:211], v[72:75]
	s_setprio 0
	s_setprio 1
	v_mfma_f32_16x16x32_bf16 v[116:119], v[160:163], v[180:183], v[116:119]
	v_mfma_f32_16x16x32_bf16 v[108:111], v[168:171], v[180:183], v[108:111]
	v_mfma_f32_16x16x32_bf16 v[100:103], v[160:163], v[188:191], v[100:103]
	v_mfma_f32_16x16x32_bf16 v[92:95], v[168:171], v[188:191], v[92:95]
	v_mfma_f32_16x16x32_bf16 v[84:87], v[160:163], v[196:199], v[84:87]
	v_mfma_f32_16x16x32_bf16 v[76:79], v[168:171], v[196:199], v[76:79]
	v_mfma_f32_16x16x32_bf16 v[68:71], v[160:163], v[204:207], v[68:71]
	v_mfma_f32_16x16x32_bf16 v[64:67], v[168:171], v[204:207], v[64:67]
	v_mfma_f32_16x16x32_bf16 v[116:119], v[164:167], v[184:187], v[116:119]
	v_mfma_f32_16x16x32_bf16 v[108:111], v[172:175], v[184:187], v[108:111]
	v_mfma_f32_16x16x32_bf16 v[100:103], v[164:167], v[192:195], v[100:103]
	v_mfma_f32_16x16x32_bf16 v[92:95], v[172:175], v[192:195], v[92:95]
	v_mfma_f32_16x16x32_bf16 v[84:87], v[164:167], v[200:203], v[84:87]
	v_mfma_f32_16x16x32_bf16 v[76:79], v[172:175], v[200:203], v[76:79]
	v_mfma_f32_16x16x32_bf16 v[68:71], v[164:167], v[208:211], v[68:71]
	v_mfma_f32_16x16x32_bf16 v[64:67], v[172:175], v[208:211], v[64:67]
	s_setprio 0
	s_barrier
	s_add_i32 s3, s43, s36
	v_lshl_add_u64 v[212:213], s[24:25], 0, v[128:129]
	s_mov_b32 m0, s3
	ds_read_b128 v[180:183], v145 offset:16384
	ds_read_b128 v[184:187], v145 offset:17408
	ds_read_b128 v[188:191], v145 offset:18432
	ds_read_b128 v[192:195], v145 offset:19456
	ds_read_b128 v[196:199], v145 offset:20480
	ds_read_b128 v[200:203], v145 offset:21504
	ds_read_b128 v[204:207], v145 offset:22528
	ds_read_b128 v[208:211], v145 offset:23552
	global_load_lds_dwordx4 v[212:213], off
	s_add_i32 m0, s3, 0x2000
	s_add_u32 s60, s24, 0xb0000
	v_lshl_add_u64 v[214:215], s[24:25], 0, v[130:131]
	s_addc_u32 s61, s25, 0
	s_add_i32 s3, s44, s36
	global_load_lds_dwordx4 v[214:215], off
	v_lshl_add_u64 v[216:217], s[60:61], 0, v[128:129]
	s_mov_b32 m0, s3
	v_lshl_add_u64 v[218:219], s[26:27], 0, v[130:131]
	global_load_lds_dwordx4 v[216:217], off
	v_lshl_add_u64 v[216:217], s[60:61], 0, v[130:131]
	s_add_i32 m0, s3, 0x2000
	s_nop 0
	global_load_lds_dwordx4 v[216:217], off
	v_lshl_add_u64 v[216:217], s[26:27], 0, v[128:129]
	s_mov_b32 m0, s37
	s_nop 0
	global_load_lds_dwordx4 v[216:217], off
	s_mov_b32 m0, s38
	s_nop 0
	global_load_lds_dwordx4 v[218:219], off
	s_waitcnt vmcnt(8)
	s_waitcnt lgkmcnt(0)
	s_barrier
; #define PG8_STAGE(bufoff, gbase, voff) do { _Pragma("unroll") for (int _i = 0; _i < 2; ++_i) \
;         __builtin_amdgcn_global_load_lds((const unsigned*)((const char*)(gbase) + (voff)[_i]), (PG8_LAS unsigned*)(lds + (bufoff) + ldsw + _i * 8192), 16, 0, 0); } while (0)
; #define PG8_LDA(dst, b, h) do { _Pragma("unroll") for (int m = 0; m < 4; ++m) _Pragma("unroll") for (int k = 0; k < 2; ++k) dst[m][k] = *(const PG8_LAS bf16x8*)(lds + PG8_SA(b, h) + aoff + m * 2048 + k * 1024); } while (0)
; #define PG8_LDB(dst, b, h) do { _Pragma("unroll") for (int n = 0; n < 2; ++n) _Pragma("unroll") for (int k = 0; k < 2; ++k) dst[n][k] = *(const PG8_LAS bf16x8*)(lds + PG8_SB(b, h) + boff + n * 2048 + k * 1024); } while (0)
; #define PG8_MMA(ai, bj, At, Bt) do { __builtin_amdgcn_s_setprio(1); _Pragma("unroll") for (int m = 0; m < 4; ++m) _Pragma("unroll") for (int n = 0; n < 2; ++n) _Pragma("unroll") for (int k = 0; k < 2; ++k) \
;         acc[ai][bj][m][n] = __builtin_amdgcn_mfma_f32_16x16x32_bf16(Bt[n][k], At[m][k], acc[ai][bj][m][n], 0, 0, 0); __builtin_amdgcn_s_setprio(0); } while (0)
; #define PG8_WAIT_V(n) asm volatile("s_waitcnt vmcnt(" #n ")" ::: "memory")
; template <class Epi, class Sched, bool ALIGN_EPI = false, bool SP2 = false>
; __device__ __forceinline__ void gemm_phase(PG8_LAS unsigned char* lds, const Gemm g, const Sched& S, const Epi& E) {
;     ...
;             PG8_LDB(B0, 0, 0); PG8_LDB(B1, 0, 1); PG8_SCHED; PG8_LDA(At, 0, 0); PG8_STAGE(PG8_SA(1, 1), a1 + hstep, voffA);
;             PG8_WAIT_V(8); PG8_WAIT_L(0); PG8_BAR; PG8_MMA(0, 0, At, B0); PG8_MMA(0, 1, At, B1); PG8_BAR; PG8_SCHED;
;             PG8_LDA(At, 0, 1); PG8_STAGE(PG8_SB(0, 0), b2, voffB); PG8_STAGE(PG8_SB(0, 1), b2 + hstep, voffB); PG8_STAGE(PG8_SA(0, 0), a2, voffA);
;             PG8_WAIT_V(8); PG8_WAIT_L(0); PG8_BAR; PG8_MMA(1, 0, At, B0); PG8_MMA(1, 1, At, B1); PG8_BAR; PG8_SCHED;
;             PG8_LDB(B0, 1, 0); PG8_LDB(B1, 1, 1); PG8_SCHED; PG8_LDA(At, 1, 0); PG8_STAGE(PG8_SA(0, 1), a2 + hstep, voffA);
;             PG8_WAIT_V(8); PG8_WAIT_L(0); PG8_BAR; PG8_MMA(0, 0, At, B0); PG8_MMA(0, 1, At, B1); PG8_BAR; PG8_SCHED;
;             PG8_LDA(At, 1, 1); PG8_STAGE(PG8_SB(1, 0), b3, voffB); PG8_STAGE(PG8_SB(1, 1), b3 + hstep, voffB); PG8_STAGE(PG8_SA(1, 0), a3, voffA);
;             PG8_WAIT_V(8); PG8_WAIT_L(0); PG8_BAR; PG8_MMA(1, 0, At, B0); PG8_MMA(1, 1, At, B1); PG8_BAR; PG8_SCHED;
	s_setprio 1
	s_waitcnt lgkmcnt(0)
	v_mfma_f32_16x16x32_bf16 v[60:63], v[136:139], v[180:183], v[60:63]
	v_mfma_f32_16x16x32_bf16 v[56:59], v[152:155], v[180:183], v[56:59]
	v_mfma_f32_16x16x32_bf16 v[48:51], v[136:139], v[188:191], v[48:51]
	v_mfma_f32_16x16x32_bf16 v[40:43], v[152:155], v[188:191], v[40:43]
	v_mfma_f32_16x16x32_bf16 v[32:35], v[136:139], v[196:199], v[32:35]
	v_mfma_f32_16x16x32_bf16 v[24:27], v[152:155], v[196:199], v[24:27]
	v_mfma_f32_16x16x32_bf16 v[16:19], v[136:139], v[204:207], v[16:19]
	v_mfma_f32_16x16x32_bf16 v[8:11], v[152:155], v[204:207], v[8:11]
	v_mfma_f32_16x16x32_bf16 v[60:63], v[148:151], v[184:187], v[60:63]
	v_mfma_f32_16x16x32_bf16 v[56:59], v[156:159], v[184:187], v[56:59]
	v_mfma_f32_16x16x32_bf16 v[48:51], v[148:151], v[192:195], v[48:51]
	v_mfma_f32_16x16x32_bf16 v[40:43], v[156:159], v[192:195], v[40:43]
	v_mfma_f32_16x16x32_bf16 v[32:35], v[148:151], v[200:203], v[32:35]
	v_mfma_f32_16x16x32_bf16 v[24:27], v[156:159], v[200:203], v[24:27]
	v_mfma_f32_16x16x32_bf16 v[16:19], v[148:151], v[208:211], v[16:19]
	v_mfma_f32_16x16x32_bf16 v[8:11], v[156:159], v[208:211], v[8:11]
	s_setprio 0
	s_setprio 1
	v_mfma_f32_16x16x32_bf16 v[52:55], v[160:163], v[180:183], v[52:55]
	v_mfma_f32_16x16x32_bf16 v[44:47], v[168:171], v[180:183], v[44:47]
	v_mfma_f32_16x16x32_bf16 v[36:39], v[160:163], v[188:191], v[36:39]
	v_mfma_f32_16x16x32_bf16 v[28:31], v[168:171], v[188:191], v[28:31]
	v_mfma_f32_16x16x32_bf16 v[20:23], v[160:163], v[196:199], v[20:23]
	v_mfma_f32_16x16x32_bf16 v[12:15], v[168:171], v[196:199], v[12:15]
	v_mfma_f32_16x16x32_bf16 v[4:7], v[160:163], v[204:207], v[4:7]
	v_mfma_f32_16x16x32_bf16 v[0:3], v[168:171], v[204:207], v[0:3]
	v_mfma_f32_16x16x32_bf16 v[52:55], v[164:167], v[184:187], v[52:55]
	v_mfma_f32_16x16x32_bf16 v[44:47], v[172:175], v[184:187], v[44:47]
	v_mfma_f32_16x16x32_bf16 v[36:39], v[164:167], v[192:195], v[36:39]
	v_mfma_f32_16x16x32_bf16 v[28:31], v[172:175], v[192:195], v[28:31]
	v_mfma_f32_16x16x32_bf16 v[20:23], v[164:167], v[200:203], v[20:23]
	v_mfma_f32_16x16x32_bf16 v[12:15], v[172:175], v[200:203], v[12:15]
	v_mfma_f32_16x16x32_bf16 v[4:7], v[164:167], v[208:211], v[4:7]
	v_mfma_f32_16x16x32_bf16 v[0:3], v[172:175], v[208:211], v[0:3]
	s_setprio 0
	s_barrier
	s_add_i32 s3, 0, 0x18000
	v_add_u32_e32 v147, s3, v141
	s_add_i32 s33, 0, 0x1c000
	ds_read_b128 v[136:139], v147
	ds_read_b128 v[148:151], v147 offset:1024
	ds_read_b128 v[152:155], v147 offset:2048
	ds_read_b128 v[156:159], v147 offset:3072
	v_add_u32_e32 v147, s33, v141
	ds_read_b128 v[160:163], v147
	ds_read_b128 v[164:167], v147 offset:1024
	ds_read_b128 v[168:171], v147 offset:2048
	ds_read_b128 v[172:175], v147 offset:3072
	s_add_u32 s26, s26, 0xb0000
	s_addc_u32 s27, s27, 0
	s_mov_b32 m0, s39
	v_lshl_add_u64 v[220:221], s[26:27], 0, v[128:129]
	ds_read_b128 v[180:183], v145 offset:32768
	ds_read_b128 v[184:187], v145 offset:33792
	ds_read_b128 v[188:191], v145 offset:34816
	ds_read_b128 v[192:195], v145 offset:35840
	ds_read_b128 v[196:199], v145 offset:36864
	ds_read_b128 v[200:203], v145 offset:37888
	ds_read_b128 v[204:207], v145 offset:38912
	ds_read_b128 v[208:211], v145 offset:39936
	global_load_lds_dwordx4 v[220:221], off
	v_lshl_add_u64 v[220:221], s[26:27], 0, v[130:131]
	s_mov_b32 m0, s40
	s_nop 0
	global_load_lds_dwordx4 v[220:221], off
	s_waitcnt vmcnt(8)
	s_waitcnt lgkmcnt(0)
	s_barrier
	s_setprio 1
	s_waitcnt lgkmcnt(0)
	v_mfma_f32_16x16x32_bf16 v[124:127], v[136:139], v[180:183], v[124:127]
	v_mfma_f32_16x16x32_bf16 v[120:123], v[152:155], v[180:183], v[120:123]
	v_mfma_f32_16x16x32_bf16 v[112:115], v[136:139], v[188:191], v[112:115]
	v_mfma_f32_16x16x32_bf16 v[104:107], v[152:155], v[188:191], v[104:107]
	v_mfma_f32_16x16x32_bf16 v[96:99], v[136:139], v[196:199], v[96:99]
	v_mfma_f32_16x16x32_bf16 v[88:91], v[152:155], v[196:199], v[88:91]
	v_mfma_f32_16x16x32_bf16 v[80:83], v[136:139], v[204:207], v[80:83]
	v_mfma_f32_16x16x32_bf16 v[72:75], v[152:155], v[204:207], v[72:75]
	v_mfma_f32_16x16x32_bf16 v[124:127], v[148:151], v[184:187], v[124:127]
	v_mfma_f32_16x16x32_bf16 v[120:123], v[156:159], v[184:187], v[120:123]
	v_mfma_f32_16x16x32_bf16 v[112:115], v[148:151], v[192:195], v[112:115]
	v_mfma_f32_16x16x32_bf16 v[104:107], v[156:159], v[192:195], v[104:107]
	v_mfma_f32_16x16x32_bf16 v[96:99], v[148:151], v[200:203], v[96:99]
	v_mfma_f32_16x16x32_bf16 v[88:91], v[156:159], v[200:203], v[88:91]
	v_mfma_f32_16x16x32_bf16 v[80:83], v[148:151], v[208:211], v[80:83]
	v_mfma_f32_16x16x32_bf16 v[72:75], v[156:159], v[208:211], v[72:75]
	s_setprio 0
	s_setprio 1
	v_mfma_f32_16x16x32_bf16 v[116:119], v[160:163], v[180:183], v[116:119]
	v_mfma_f32_16x16x32_bf16 v[108:111], v[168:171], v[180:183], v[108:111]
	v_mfma_f32_16x16x32_bf16 v[100:103], v[160:163], v[188:191], v[100:103]
	v_mfma_f32_16x16x32_bf16 v[92:95], v[168:171], v[188:191], v[92:95]
	v_mfma_f32_16x16x32_bf16 v[84:87], v[160:163], v[196:199], v[84:87]
	v_mfma_f32_16x16x32_bf16 v[76:79], v[168:171], v[196:199], v[76:79]
	v_mfma_f32_16x16x32_bf16 v[68:71], v[160:163], v[204:207], v[68:71]
	v_mfma_f32_16x16x32_bf16 v[64:67], v[168:171], v[204:207], v[64:67]
	v_mfma_f32_16x16x32_bf16 v[116:119], v[164:167], v[184:187], v[116:119]
	v_mfma_f32_16x16x32_bf16 v[108:111], v[172:175], v[184:187], v[108:111]
	v_mfma_f32_16x16x32_bf16 v[100:103], v[164:167], v[192:195], v[100:103]
	v_mfma_f32_16x16x32_bf16 v[92:95], v[172:175], v[192:195], v[92:95]
	v_mfma_f32_16x16x32_bf16 v[84:87], v[164:167], v[200:203], v[84:87]
	v_mfma_f32_16x16x32_bf16 v[76:79], v[172:175], v[200:203], v[76:79]
	v_mfma_f32_16x16x32_bf16 v[68:71], v[164:167], v[208:211], v[68:71]
	v_mfma_f32_16x16x32_bf16 v[64:67], v[172:175], v[208:211], v[64:67]
	s_setprio 0
	s_barrier
; #define PG8_STAGE(bufoff, gbase, voff) do { _Pragma("unroll") for (int _i = 0; _i < 2; ++_i) \
;         __builtin_amdgcn_global_load_lds((const unsigned*)((const char*)(gbase) + (voff)[_i]), (PG8_LAS unsigned*)(lds + (bufoff) + ldsw + _i * 8192), 16, 0, 0); } while (0)
; #define PG8_LDA(dst, b, h) do { _Pragma("unroll") for (int m = 0; m < 4; ++m) _Pragma("unroll") for (int k = 0; k < 2; ++k) dst[m][k] = *(const PG8_LAS bf16x8*)(lds + PG8_SA(b, h) + aoff + m * 2048 + k * 1024); } while (0)
; #define PG8_LDB(dst, b, h) do { _Pragma("unroll") for (int n = 0; n < 2; ++n) _Pragma("unroll") for (int k = 0; k < 2; ++k) dst[n][k] = *(const PG8_LAS bf16x8*)(lds + PG8_SB(b, h) + boff + n * 2048 + k * 1024); } while (0)
; #define PG8_MMA(ai, bj, At, Bt) do { __builtin_amdgcn_s_setprio(1); _Pragma("unroll") for (int m = 0; m < 4; ++m) _Pragma("unroll") for (int n = 0; n < 2; ++n) _Pragma("unroll") for (int k = 0; k < 2; ++k) \
;         acc[ai][bj][m][n] = __builtin_amdgcn_mfma_f32_16x16x32_bf16(Bt[n][k], At[m][k], acc[ai][bj][m][n], 0, 0, 0); __builtin_amdgcn_s_setprio(0); } while (0)
; #define PG8_WAIT_V(n) asm volatile("s_waitcnt vmcnt(" #n ")" ::: "memory")
; #define PG8_WAIT_L(n) asm volatile("s_waitcnt lgkmcnt(" #n ")" ::: "memory")
; #define PG8_BAR __builtin_amdgcn_s_barrier()
; #define PG8_SCHED __builtin_amdgcn_sched_barrier(0)
; template <class Epi, class Sched, bool ALIGN_EPI = false, bool SP2 = false>
; __device__ __forceinline__ void gemm_phase(PG8_LAS unsigned char* lds, const Gemm g, const Sched& S, const Epi& E) {
;     ...
;         for (int t = 0; t < nt; t += 2) {
;             const bool last = (t == nt - 2);
;     ...
;             PG8_LDB(B0, 1, 0); PG8_LDB(B1, 1, 1); PG8_SCHED; PG8_LDA(At, 1, 0); PG8_STAGE(PG8_SA(0, 1), a2 + hstep, voffA);
;             PG8_WAIT_V(8); PG8_WAIT_L(0); PG8_BAR; PG8_MMA(0, 0, At, B0); PG8_MMA(0, 1, At, B1); PG8_BAR; PG8_SCHED;
;             PG8_LDA(At, 1, 1); PG8_STAGE(PG8_SB(1, 0), b3, voffB); PG8_STAGE(PG8_SB(1, 1), b3 + hstep, voffB); PG8_STAGE(PG8_SA(1, 0), a3, voffA);
;             PG8_WAIT_V(8); PG8_WAIT_L(0); PG8_BAR; PG8_MMA(1, 0, At, B0); PG8_MMA(1, 1, At, B1); PG8_BAR; PG8_SCHED;
	s_add_i32 s3, s3, s36
	v_lshl_add_u64 v[212:213], v[212:213], 0, s[16:17]
	s_mov_b32 m0, s3
	ds_read_b128 v[180:183], v145 offset:49152
	ds_read_b128 v[184:187], v145 offset:50176
	ds_read_b128 v[188:191], v145 offset:51200
	ds_read_b128 v[192:195], v145 offset:52224
	ds_read_b128 v[196:199], v145 offset:53248
	ds_read_b128 v[200:203], v145 offset:54272
	ds_read_b128 v[204:207], v145 offset:55296
	ds_read_b128 v[208:211], v145 offset:56320
	global_load_lds_dwordx4 v[212:213], off
	s_add_i32 m0, s3, 0x2000
	s_add_u32 s24, s24, 0xb0080
	v_lshl_add_u64 v[212:213], v[214:215], 0, s[16:17]
	s_addc_u32 s25, s25, 0
	s_add_i32 s3, s33, s36
	global_load_lds_dwordx4 v[212:213], off
	v_lshl_add_u64 v[212:213], s[24:25], 0, v[128:129]
	s_mov_b32 m0, s3
	s_nop 0
	global_load_lds_dwordx4 v[212:213], off
	v_lshl_add_u64 v[212:213], s[24:25], 0, v[130:131]
	s_add_i32 m0, s3, 0x2000
	s_nop 0
	global_load_lds_dwordx4 v[212:213], off
	v_lshl_add_u64 v[212:213], v[216:217], 0, s[16:17]
	s_mov_b32 m0, s41
	s_nop 0
	global_load_lds_dwordx4 v[212:213], off
	v_lshl_add_u64 v[212:213], v[218:219], 0, s[16:17]
	s_mov_b32 m0, s42
	s_nop 0
	global_load_lds_dwordx4 v[212:213], off
	s_waitcnt vmcnt(8)
	s_waitcnt lgkmcnt(0)
	s_barrier
	s_setprio 1
	s_waitcnt lgkmcnt(0)
	v_mfma_f32_16x16x32_bf16 v[60:63], v[136:139], v[180:183], v[60:63]
	v_mfma_f32_16x16x32_bf16 v[56:59], v[152:155], v[180:183], v[56:59]
	v_mfma_f32_16x16x32_bf16 v[48:51], v[136:139], v[188:191], v[48:51]
	v_mfma_f32_16x16x32_bf16 v[40:43], v[152:155], v[188:191], v[40:43]
	v_mfma_f32_16x16x32_bf16 v[32:35], v[136:139], v[196:199], v[32:35]
	v_mfma_f32_16x16x32_bf16 v[24:27], v[152:155], v[196:199], v[24:27]
	v_mfma_f32_16x16x32_bf16 v[16:19], v[136:139], v[204:207], v[16:19]
	v_mfma_f32_16x16x32_bf16 v[8:11], v[152:155], v[204:207], v[8:11]
	v_mfma_f32_16x16x32_bf16 v[60:63], v[148:151], v[184:187], v[60:63]
	v_mfma_f32_16x16x32_bf16 v[56:59], v[156:159], v[184:187], v[56:59]
	v_mfma_f32_16x16x32_bf16 v[48:51], v[148:151], v[192:195], v[48:51]
	v_mfma_f32_16x16x32_bf16 v[40:43], v[156:159], v[192:195], v[40:43]
	v_mfma_f32_16x16x32_bf16 v[32:35], v[148:151], v[200:203], v[32:35]
	v_mfma_f32_16x16x32_bf16 v[24:27], v[156:159], v[200:203], v[24:27]
	v_mfma_f32_16x16x32_bf16 v[16:19], v[148:151], v[208:211], v[16:19]
	v_mfma_f32_16x16x32_bf16 v[8:11], v[156:159], v[208:211], v[8:11]
	s_setprio 0
	s_setprio 1
	v_mfma_f32_16x16x32_bf16 v[52:55], v[160:163], v[180:183], v[52:55]
	v_mfma_f32_16x16x32_bf16 v[44:47], v[168:171], v[180:183], v[44:47]
	v_mfma_f32_16x16x32_bf16 v[36:39], v[160:163], v[188:191], v[36:39]
	v_mfma_f32_16x16x32_bf16 v[28:31], v[168:171], v[188:191], v[28:31]
	v_mfma_f32_16x16x32_bf16 v[20:23], v[160:163], v[196:199], v[20:23]
	v_mfma_f32_16x16x32_bf16 v[12:15], v[168:171], v[196:199], v[12:15]
	v_mfma_f32_16x16x32_bf16 v[4:7], v[160:163], v[204:207], v[4:7]
	v_mfma_f32_16x16x32_bf16 v[0:3], v[168:171], v[204:207], v[0:3]
	v_mfma_f32_16x16x32_bf16 v[52:55], v[164:167], v[184:187], v[52:55]
	v_mfma_f32_16x16x32_bf16 v[44:47], v[172:175], v[184:187], v[44:47]
	v_mfma_f32_16x16x32_bf16 v[36:39], v[164:167], v[192:195], v[36:39]
	v_mfma_f32_16x16x32_bf16 v[28:31], v[172:175], v[192:195], v[28:31]
	v_mfma_f32_16x16x32_bf16 v[20:23], v[164:167], v[200:203], v[20:23]
	v_mfma_f32_16x16x32_bf16 v[12:15], v[172:175], v[200:203], v[12:15]
	v_mfma_f32_16x16x32_bf16 v[4:7], v[164:167], v[208:211], v[4:7]
	v_mfma_f32_16x16x32_bf16 v[0:3], v[172:175], v[208:211], v[0:3]
	s_setprio 0
	s_barrier
	s_add_i32 s51, s51, 2
	s_add_u32 s22, s22, 0x100
	s_addc_u32 s23, s23, 0
	s_add_u32 s49, s49, 0x100
	s_addc_u32 s50, s50, 0
	s_cmp_gt_u32 s51, 19
	s_cbranch_scc0 .LBB0_1440
	s_and_b32 s100, s2, 15
	v_readfirstlane_b32 s101, v178
	s_lshl_b32 s98, s100, 18
	s_lshr_b32 s101, s101, 6
	s_lshl_b32 s99, s101, 15
	s_add_u32 s98, s98, s99
	s_lshl_b32 s100, s100, 3
	s_add_u32 s100, s100, s101
	s_lshl_b32 s100, s100, 2
	s_add_u32 s98, s54, s98
	s_addc_u32 s99, s55, 0
	s_add_u32 s98, s98, 0x9a00000
	s_addc_u32 s99, s99, 0
	s_add_u32 s100, s54, s100
	s_addc_u32 s101, s55, 0
	s_add_u32 s100, s100, 0x22a2000
	s_addc_u32 s101, s101, 0
	v_lshlrev_b32_e32 v160, 4, v176
	v_mov_b32_e32 v161, 0
	s_cmp_lt_u32 s2, 16
	s_cbranch_scc1 .Lsk_reader
; #define PG8_BAR __builtin_amdgcn_s_barrier()
; template <class Epi, class Sched, bool ALIGN_EPI = false, bool SP2 = false>
; __device__ __forceinline__ void gemm_phase(PG8_LAS unsigned char* lds, const Gemm g, const Sched& S, const Epi& E) {
;     ...
;         }
;         if constexpr (ALIGN_EPI) { if (wr == 0) PG8_BAR; }
;         if constexpr (!Epi::AFTER_DRAIN) { E(acc, cur, wr, wc, fr, fq); S.done(cur); }
;         if (!has_next) break;
	global_store_dwordx4 v160, v[0:3], s[98:99]
	s_add_u32 s98, s98, 0x400
	s_addc_u32 s99, s99, 0
	global_store_dwordx4 v160, v[4:7], s[98:99]
	s_add_u32 s98, s98, 0x400
	s_addc_u32 s99, s99, 0
	global_store_dwordx4 v160, v[8:11], s[98:99]
	s_add_u32 s98, s98, 0x400
	s_addc_u32 s99, s99, 0
	global_store_dwordx4 v160, v[12:15], s[98:99]
	s_add_u32 s98, s98, 0x400
	s_addc_u32 s99, s99, 0
	global_store_dwordx4 v160, v[16:19], s[98:99]
	s_add_u32 s98, s98, 0x400
	s_addc_u32 s99, s99, 0
	global_store_dwordx4 v160, v[20:23], s[98:99]
	s_add_u32 s98, s98, 0x400
	s_addc_u32 s99, s99, 0
	global_store_dwordx4 v160, v[24:27], s[98:99]
	s_add_u32 s98, s98, 0x400
	s_addc_u32 s99, s99, 0
	global_store_dwordx4 v160, v[28:31], s[98:99]
	s_add_u32 s98, s98, 0x400
	s_addc_u32 s99, s99, 0
	global_store_dwordx4 v160, v[32:35], s[98:99]
	s_add_u32 s98, s98, 0x400
	s_addc_u32 s99, s99, 0
	global_store_dwordx4 v160, v[36:39], s[98:99]
	s_add_u32 s98, s98, 0x400
	s_addc_u32 s99, s99, 0
	global_store_dwordx4 v160, v[40:43], s[98:99]
	s_add_u32 s98, s98, 0x400
	s_addc_u32 s99, s99, 0
	global_store_dwordx4 v160, v[44:47], s[98:99]
	s_add_u32 s98, s98, 0x400
	s_addc_u32 s99, s99, 0
	global_store_dwordx4 v160, v[48:51], s[98:99]
	s_add_u32 s98, s98, 0x400
	s_addc_u32 s99, s99, 0
	global_store_dwordx4 v160, v[52:55], s[98:99]
	s_add_u32 s98, s98, 0x400
	s_addc_u32 s99, s99, 0
	global_store_dwordx4 v160, v[56:59], s[98:99]
	s_add_u32 s98, s98, 0x400
	s_addc_u32 s99, s99, 0
	global_store_dwordx4 v160, v[60:63], s[98:99]
	s_add_u32 s98, s98, 0x400
	s_addc_u32 s99, s99, 0
	global_store_dwordx4 v160, v[64:67], s[98:99]
	s_add_u32 s98, s98, 0x400
	s_addc_u32 s99, s99, 0
	global_store_dwordx4 v160, v[68:71], s[98:99]
	s_add_u32 s98, s98, 0x400
	s_addc_u32 s99, s99, 0
	global_store_dwordx4 v160, v[72:75], s[98:99]
	s_add_u32 s98, s98, 0x400
	s_addc_u32 s99, s99, 0
	global_store_dwordx4 v160, v[76:79], s[98:99]
	s_add_u32 s98, s98, 0x400
	s_addc_u32 s99, s99, 0
	global_store_dwordx4 v160, v[80:83], s[98:99]
	s_add_u32 s98, s98, 0x400
	s_addc_u32 s99, s99, 0
	global_store_dwordx4 v160, v[84:87], s[98:99]
	s_add_u32 s98, s98, 0x400
	s_addc_u32 s99, s99, 0
	global_store_dwordx4 v160, v[88:91], s[98:99]
	s_add_u32 s98, s98, 0x400
	s_addc_u32 s99, s99, 0
	global_store_dwordx4 v160, v[92:95], s[98:99]
	s_add_u32 s98, s98, 0x400
	s_addc_u32 s99, s99, 0
	global_store_dwordx4 v160, v[96:99], s[98:99]
	s_add_u32 s98, s98, 0x400
	s_addc_u32 s99, s99, 0
	global_store_dwordx4 v160, v[100:103], s[98:99]
	s_add_u32 s98, s98, 0x400
	s_addc_u32 s99, s99, 0
	global_store_dwordx4 v160, v[104:107], s[98:99]
	s_add_u32 s98, s98, 0x400
	s_addc_u32 s99, s99, 0
	global_store_dwordx4 v160, v[108:111], s[98:99]
	s_add_u32 s98, s98, 0x400
	s_addc_u32 s99, s99, 0
	global_store_dwordx4 v160, v[112:115], s[98:99]
	s_add_u32 s98, s98, 0x400
	s_addc_u32 s99, s99, 0
	global_store_dwordx4 v160, v[116:119], s[98:99]
	s_add_u32 s98, s98, 0x400
	s_addc_u32 s99, s99, 0
	global_store_dwordx4 v160, v[120:123], s[98:99]
	s_add_u32 s98, s98, 0x400
	s_addc_u32 s99, s99, 0
	global_store_dwordx4 v160, v[124:127], s[98:99]
	s_add_u32 s98, s98, 0x400
	s_addc_u32 s99, s99, 0
	s_waitcnt vmcnt(0)
	buffer_wbl2 sc1
	s_waitcnt vmcnt(0)
	s_mov_b64 exec, 1
	v_mov_b32_e32 v162, 1
	global_atomic_add v161, v162, s[100:101]
	s_mov_b64 exec, -1
	s_branch .LBB0_1428
.Lsk_reader:
	v_mov_b32_e32 v162, 0
.Lsk_loop:
	global_load_dword v163, v161, s[100:101] sc1
	s_waitcnt vmcnt(0)
	v_cmp_ne_u32_e32 vcc, 0, v163
	s_cbranch_vccnz .Lsk_go
	v_add_u32_e32 v162, 1, v162
	v_cmp_gt_u32_e32 vcc, 0x100000, v162
	s_sleep 1
	s_cbranch_vccnz .Lsk_loop
.Lsk_go:
	buffer_inv sc1
	s_waitcnt vmcnt(0)
	global_load_dwordx4 v[180:183], v160, s[98:99]
	s_add_u32 s98, s98, 0x400
	s_addc_u32 s99, s99, 0
	global_load_dwordx4 v[184:187], v160, s[98:99]
	s_add_u32 s98, s98, 0x400
	s_addc_u32 s99, s99, 0
	global_load_dwordx4 v[188:191], v160, s[98:99]
	s_add_u32 s98, s98, 0x400
	s_addc_u32 s99, s99, 0
	global_load_dwordx4 v[192:195], v160, s[98:99]
	s_add_u32 s98, s98, 0x400
	s_addc_u32 s99, s99, 0
	global_load_dwordx4 v[196:199], v160, s[98:99]
	s_add_u32 s98, s98, 0x400
	s_addc_u32 s99, s99, 0
	global_load_dwordx4 v[200:203], v160, s[98:99]
	s_add_u32 s98, s98, 0x400
	s_addc_u32 s99, s99, 0
	global_load_dwordx4 v[204:207], v160, s[98:99]
	s_add_u32 s98, s98, 0x400
	s_addc_u32 s99, s99, 0
	global_load_dwordx4 v[208:211], v160, s[98:99]
	s_add_u32 s98, s98, 0x400
	s_addc_u32 s99, s99, 0
	global_load_dwordx4 v[212:215], v160, s[98:99]
	s_add_u32 s98, s98, 0x400
	s_addc_u32 s99, s99, 0
	global_load_dwordx4 v[216:219], v160, s[98:99]
	s_add_u32 s98, s98, 0x400
	s_addc_u32 s99, s99, 0
	global_load_dwordx4 v[220:223], v160, s[98:99]
	s_add_u32 s98, s98, 0x400
	s_addc_u32 s99, s99, 0
	global_load_dwordx4 v[224:227], v160, s[98:99]
	s_add_u32 s98, s98, 0x400
	s_addc_u32 s99, s99, 0
	global_load_dwordx4 v[228:231], v160, s[98:99]
	s_add_u32 s98, s98, 0x400
	s_addc_u32 s99, s99, 0
	global_load_dwordx4 v[232:235], v160, s[98:99]
	s_add_u32 s98, s98, 0x400
	s_addc_u32 s99, s99, 0
	global_load_dwordx4 v[236:239], v160, s[98:99]
	s_add_u32 s98, s98, 0x400
	s_addc_u32 s99, s99, 0
	global_load_dwordx4 v[240:243], v160, s[98:99]
	s_add_u32 s98, s98, 0x400
	s_addc_u32 s99, s99, 0
	s_waitcnt vmcnt(8)
; #define PG8_BAR __builtin_amdgcn_s_barrier()
; template <class Epi, class Sched, bool ALIGN_EPI = false, bool SP2 = false>
; __device__ __forceinline__ void gemm_phase(PG8_LAS unsigned char* lds, const Gemm g, const Sched& S, const Epi& E) {
;     ...
;         }
;         if constexpr (ALIGN_EPI) { if (wr == 0) PG8_BAR; }
;         if constexpr (!Epi::AFTER_DRAIN) { E(acc, cur, wr, wc, fr, fq); S.done(cur); }
;         if (!has_next) break;
	v_add_f32_e32 v0, v0, v180
	v_add_f32_e32 v1, v1, v181
	v_add_f32_e32 v2, v2, v182
	v_add_f32_e32 v3, v3, v183
	v_add_f32_e32 v4, v4, v184
	v_add_f32_e32 v5, v5, v185
	v_add_f32_e32 v6, v6, v186
	v_add_f32_e32 v7, v7, v187
	v_add_f32_e32 v8, v8, v188
	v_add_f32_e32 v9, v9, v189
	v_add_f32_e32 v10, v10, v190
	v_add_f32_e32 v11, v11, v191
	v_add_f32_e32 v12, v12, v192
	v_add_f32_e32 v13, v13, v193
	v_add_f32_e32 v14, v14, v194
	v_add_f32_e32 v15, v15, v195
	v_add_f32_e32 v16, v16, v196
	v_add_f32_e32 v17, v17, v197
	v_add_f32_e32 v18, v18, v198
	v_add_f32_e32 v19, v19, v199
	v_add_f32_e32 v20, v20, v200
	v_add_f32_e32 v21, v21, v201
	v_add_f32_e32 v22, v22, v202
	v_add_f32_e32 v23, v23, v203
	v_add_f32_e32 v24, v24, v204
	v_add_f32_e32 v25, v25, v205
	v_add_f32_e32 v26, v26, v206
	v_add_f32_e32 v27, v27, v207
	v_add_f32_e32 v28, v28, v208
	v_add_f32_e32 v29, v29, v209
	v_add_f32_e32 v30, v30, v210
	v_add_f32_e32 v31, v31, v211
	global_load_dwordx4 v[180:183], v160, s[98:99]
	s_add_u32 s98, s98, 0x400
	s_addc_u32 s99, s99, 0
	global_load_dwordx4 v[184:187], v160, s[98:99]
	s_add_u32 s98, s98, 0x400
	s_addc_u32 s99, s99, 0
	global_load_dwordx4 v[188:191], v160, s[98:99]
	s_add_u32 s98, s98, 0x400
	s_addc_u32 s99, s99, 0
	global_load_dwordx4 v[192:195], v160, s[98:99]
	s_add_u32 s98, s98, 0x400
	s_addc_u32 s99, s99, 0
	global_load_dwordx4 v[196:199], v160, s[98:99]
	s_add_u32 s98, s98, 0x400
	s_addc_u32 s99, s99, 0
	global_load_dwordx4 v[200:203], v160, s[98:99]
	s_add_u32 s98, s98, 0x400
	s_addc_u32 s99, s99, 0
	global_load_dwordx4 v[204:207], v160, s[98:99]
	s_add_u32 s98, s98, 0x400
	s_addc_u32 s99, s99, 0
	global_load_dwordx4 v[208:211], v160, s[98:99]
	s_add_u32 s98, s98, 0x400
	s_addc_u32 s99, s99, 0
	s_waitcnt vmcnt(8)
	v_add_f32_e32 v32, v32, v212
	v_add_f32_e32 v33, v33, v213
	v_add_f32_e32 v34, v34, v214
	v_add_f32_e32 v35, v35, v215
	v_add_f32_e32 v36, v36, v216
	v_add_f32_e32 v37, v37, v217
	v_add_f32_e32 v38, v38, v218
	v_add_f32_e32 v39, v39, v219
	v_add_f32_e32 v40, v40, v220
	v_add_f32_e32 v41, v41, v221
	v_add_f32_e32 v42, v42, v222
	v_add_f32_e32 v43, v43, v223
	v_add_f32_e32 v44, v44, v224
	v_add_f32_e32 v45, v45, v225
	v_add_f32_e32 v46, v46, v226
	v_add_f32_e32 v47, v47, v227
	v_add_f32_e32 v48, v48, v228
	v_add_f32_e32 v49, v49, v229
	v_add_f32_e32 v50, v50, v230
	v_add_f32_e32 v51, v51, v231
	v_add_f32_e32 v52, v52, v232
	v_add_f32_e32 v53, v53, v233
	v_add_f32_e32 v54, v54, v234
	v_add_f32_e32 v55, v55, v235
	v_add_f32_e32 v56, v56, v236
	v_add_f32_e32 v57, v57, v237
	v_add_f32_e32 v58, v58, v238
	v_add_f32_e32 v59, v59, v239
	v_add_f32_e32 v60, v60, v240
	v_add_f32_e32 v61, v61, v241
	v_add_f32_e32 v62, v62, v242
	v_add_f32_e32 v63, v63, v243
	global_load_dwordx4 v[212:215], v160, s[98:99]
	s_add_u32 s98, s98, 0x400
	s_addc_u32 s99, s99, 0
	global_load_dwordx4 v[216:219], v160, s[98:99]
	s_add_u32 s98, s98, 0x400
	s_addc_u32 s99, s99, 0
	global_load_dwordx4 v[220:223], v160, s[98:99]
	s_add_u32 s98, s98, 0x400
	s_addc_u32 s99, s99, 0
	global_load_dwordx4 v[224:227], v160, s[98:99]
	s_add_u32 s98, s98, 0x400
	s_addc_u32 s99, s99, 0
	global_load_dwordx4 v[228:231], v160, s[98:99]
	s_add_u32 s98, s98, 0x400
	s_addc_u32 s99, s99, 0
	global_load_dwordx4 v[232:235], v160, s[98:99]
	s_add_u32 s98, s98, 0x400
	s_addc_u32 s99, s99, 0
	global_load_dwordx4 v[236:239], v160, s[98:99]
	s_add_u32 s98, s98, 0x400
	s_addc_u32 s99, s99, 0
	global_load_dwordx4 v[240:243], v160, s[98:99]
	s_add_u32 s98, s98, 0x400
	s_addc_u32 s99, s99, 0
	s_waitcnt vmcnt(8)
; __device__ __forceinline__ u32x2 pk4(f32x4 v) { u32x2 w; w.x = cvt_pk_bf16(v[0], v[1]); w.y = cvt_pk_bf16(v[2], v[3]); return w; }
; __device__ __forceinline__ f32x4 up4(u32x2 w) { return (f32x4){bf_lo(w.x), bf_hi(w.x), bf_lo(w.y), bf_hi(w.y)}; }
;     __device__ __forceinline__ void operator()(const AccT& acc, const pg8::Unit& u, int wr, int wc, int fr, int fq) const {
;         const int col0 = u.pn * 256 + wc * 32 + 4 * fq, row0 = row_base + u.pm * 256 + wr * 64 + fr;
; #pragma unroll
;         for (int ai = 0; ai < 2; ++ai)
; #pragma unroll
;             for (int m = 0; m < 4; ++m) { const int row = row0 + ai * 128 + m * 16; float ss = 0.f;
; #pragma unroll
;                 for (int bj = 0; bj < 2; ++bj)
; #pragma unroll
;                     for (int n = 0; n < 2; ++n) { f32x4 v = acc[ai][bj][m][n]; const size_t idx = (size_t)row * 1024 + col0 + bj * 128 + n * 16;
;                         if (MODE == 0) v = v * up4(*(const u32x2*)(io + idx));
;                         else if (MODE == 1) v = up4(*(const u32x2*)(io + idx)) + up4(*(const u32x2*)(g2 + idx)) * v;
;                         else ss += (v[0] * v[0] + v[1] * v[1]) + (v[2] * v[2] + v[3] * v[3]);
;                         if (!DRYE || v[0] == 123.456f) *(u32x2*)(io + idx) = pk4(v); }
;                 if (MODE == 2 && !DRYE) { ss += __shfl_xor(ss, 16); ss += __shfl_xor(ss, 32); if (fq == 0) atomicAdd(rowss + row, ss); } }
	v_add_f32_e32 v64, v64, v180
	v_add_f32_e32 v65, v65, v181
	v_add_f32_e32 v66, v66, v182
	v_add_f32_e32 v67, v67, v183
	v_add_f32_e32 v68, v68, v184
	v_add_f32_e32 v69, v69, v185
	v_add_f32_e32 v70, v70, v186
	v_add_f32_e32 v71, v71, v187
	v_add_f32_e32 v72, v72, v188
	v_add_f32_e32 v73, v73, v189
	v_add_f32_e32 v74, v74, v190
	v_add_f32_e32 v75, v75, v191
	v_add_f32_e32 v76, v76, v192
	v_add_f32_e32 v77, v77, v193
	v_add_f32_e32 v78, v78, v194
	v_add_f32_e32 v79, v79, v195
	v_add_f32_e32 v80, v80, v196
	v_add_f32_e32 v81, v81, v197
	v_add_f32_e32 v82, v82, v198
	v_add_f32_e32 v83, v83, v199
	v_add_f32_e32 v84, v84, v200
	v_add_f32_e32 v85, v85, v201
	v_add_f32_e32 v86, v86, v202
	v_add_f32_e32 v87, v87, v203
	v_add_f32_e32 v88, v88, v204
	v_add_f32_e32 v89, v89, v205
	v_add_f32_e32 v90, v90, v206
	v_add_f32_e32 v91, v91, v207
	v_add_f32_e32 v92, v92, v208
	v_add_f32_e32 v93, v93, v209
	v_add_f32_e32 v94, v94, v210
	v_add_f32_e32 v95, v95, v211
	s_waitcnt vmcnt(0)
	v_add_f32_e32 v96, v96, v212
	v_add_f32_e32 v97, v97, v213
	v_add_f32_e32 v98, v98, v214
	v_add_f32_e32 v99, v99, v215
	v_add_f32_e32 v100, v100, v216
	v_add_f32_e32 v101, v101, v217
	v_add_f32_e32 v102, v102, v218
	v_add_f32_e32 v103, v103, v219
	v_add_f32_e32 v104, v104, v220
	v_add_f32_e32 v105, v105, v221
	v_add_f32_e32 v106, v106, v222
	v_add_f32_e32 v107, v107, v223
	v_add_f32_e32 v108, v108, v224
	v_add_f32_e32 v109, v109, v225
	v_add_f32_e32 v110, v110, v226
	v_add_f32_e32 v111, v111, v227
	v_add_f32_e32 v112, v112, v228
	v_add_f32_e32 v113, v113, v229
	v_add_f32_e32 v114, v114, v230
	v_add_f32_e32 v115, v115, v231
	v_add_f32_e32 v116, v116, v232
	v_add_f32_e32 v117, v117, v233
	v_add_f32_e32 v118, v118, v234
	v_add_f32_e32 v119, v119, v235
	v_add_f32_e32 v120, v120, v236
	v_add_f32_e32 v121, v121, v237
	v_add_f32_e32 v122, v122, v238
	v_add_f32_e32 v123, v123, v239
	v_add_f32_e32 v124, v124, v240
	v_add_f32_e32 v125, v125, v241
	v_add_f32_e32 v126, v126, v242
	v_add_f32_e32 v127, v127, v243
	v_and_b32_e32 v147, 64, v146
	v_xor_b32_e32 v139, 16, v146
	v_add_u32_e32 v147, 64, v147
	v_cmp_lt_i32_e32 vcc, v139, v147
	v_lshl_add_u32 v149, s47, 8, v140
	v_add_u32_e32 v138, 0x4000, v149
	v_cndmask_b32_e32 v139, v146, v139, vcc
	v_lshlrev_b32_e32 v148, 2, v139
	v_xor_b32_e32 v139, 32, v146
	v_cmp_lt_i32_e32 vcc, v139, v147
	v_lshl_or_b32 v136, s48, 8, v142
	v_mul_f32_e32 v152, v125, v125
	v_cndmask_b32_e32 v139, v146, v139, vcc
	v_lshlrev_b32_e32 v147, 2, v139
	v_ashrrev_i32_e32 v139, 31, v138
	v_lshlrev_b64 v[150:151], 11, v[138:139]
	v_mul_f32_e32 v153, v127, v127
	v_ashrrev_i32_e32 v137, 31, v136
	v_fmac_f32_e32 v152, v124, v124
	v_fmac_f32_e32 v153, v126, v126
	v_cvt_pk_bf16_f32 v124, v124, v125
	v_cvt_pk_bf16_f32 v125, v126, v127
	v_lshl_add_u64 v[126:127], s[10:11], 0, v[150:151]
	v_lshl_add_u64 v[126:127], v[136:137], 1, v[126:127]
	global_store_dwordx2 v[126:127], v[124:125], off
	v_mul_f32_e32 v124, v121, v121
	v_mul_f32_e32 v125, v123, v123
	v_fmac_f32_e32 v124, v120, v120
	v_fmac_f32_e32 v125, v122, v122
	v_add_f32_e32 v124, v124, v125
	v_cvt_pk_bf16_f32 v120, v120, v121
	v_mul_f32_e32 v121, v117, v117
	v_mul_f32_e32 v125, v119, v119
	v_add_f32_e32 v152, v152, v153
	v_fmac_f32_e32 v121, v116, v116
	v_fmac_f32_e32 v125, v118, v118
	v_add_f32_e32 v124, v152, v124
	v_add_f32_e32 v121, v121, v125
	v_add_f32_e32 v121, v124, v121
	v_mul_f32_e32 v124, v109, v109
	v_mul_f32_e32 v125, v111, v111
	v_fmac_f32_e32 v124, v108, v108
	v_fmac_f32_e32 v125, v110, v110
	v_add_f32_e32 v124, v124, v125
	v_add_f32_e32 v124, v121, v124
	ds_bpermute_b32 v125, v148, v124
	v_cvt_pk_bf16_f32 v121, v122, v123
	global_store_dwordx2 v[126:127], v[120:121], off offset:32
	v_cvt_pk_bf16_f32 v120, v116, v117
	v_cvt_pk_bf16_f32 v121, v118, v119
	s_waitcnt lgkmcnt(0)
	v_add_f32_e32 v116, v124, v125
	ds_bpermute_b32 v117, v147, v116
	v_cvt_pk_bf16_f32 v108, v108, v109
	v_cvt_pk_bf16_f32 v109, v110, v111
	global_store_dwordx2 v[126:127], v[120:121], off offset:256
	global_store_dwordx2 v[126:127], v[108:109], off offset:288
	s_and_saveexec_b64 s[22:23], s[0:1]
	s_cbranch_execz .LBB0_1443
	v_lshl_add_u64 v[108:109], v[138:139], 2, s[14:15]
	s_waitcnt lgkmcnt(0)
	v_add_f32_e32 v110, v116, v117
	global_atomic_add_f32 v[108:109], v110, off
